# init phase fast path: x load stays in flight while the modulation rows are fetched (one round trip per iteration instead of two)
# speedup vs baseline: 1.0122x; 1.0032x over previous
.LBB0_40:
	v_lshl_add_u64 v[8:9], s[76:77], 0, v[2:3]
	global_load_dwordx4 v[8:11], v[8:9], off nt
	v_and_b32_e32 v16, 0x3fc, v6
	v_alignbit_b32 v17, v1, v0, 19
	v_mov_b64_e32 v[14:15], s[34:35]
	v_mad_u64_u32 v[14:15], s[0:1], v17, s15, v[14:15]
	v_lshlrev_b32_e32 v32, 2, v16
	v_lshl_add_u64 v[16:17], v[14:15], 0, v[32:33]
	v_lshl_add_u64 v[12:13], s[68:69], 0, v[2:3]
	v_add_co_u32_e32 v14, vcc, s25, v16
	v_lshl_add_u64 v[0:1], v[0:1], 0, s[16:17]
	s_nop 0
	v_addc_co_u32_e32 v15, vcc, 0, v17, vcc
	s_mov_b64 s[0:1], 0x7fffff
	v_cmp_lt_u64_e32 vcc, s[0:1], v[0:1]
	v_lshl_add_u64 v[2:3], v[2:3], 0, s[18:19]
	v_lshl_add_u64 v[6:7], v[6:7], 0, s[22:23]
	s_or_b64 s[40:41], vcc, s[40:41]
	v_readlane_b32 s0, v252, 8
	s_cmpk_eq_i32 s0, 0x800
	s_cbranch_scc1 .Linit_nocopy
	s_waitcnt vmcnt(0)
	global_store_dwordx4 v[12:13], v[8:11], off
